# row passes: loop-invariant gain-vector loads hoisted out of the row loop (removes 8 serialized L2 round trips + store-ack waits per row), on top of slot conversion
# speedup vs baseline: 1.0327x; 1.0327x over previous
.LBB0_61:
	v_mov_b32_e32 v1, v214
	s_mov_b64 s[4:5], s[0:1]
	v_readfirstlane_b32 s3, v1
	s_ashr_i32 s3, s3, 6
	s_add_i32 s10, s3, s81
	s_mov_b64 s[6:7], s[0:1]
	s_mov_b64 s[12:13], s[0:1]
	s_cmpk_gt_i32 s10, 0x1fff
	v_mbcnt_lo_u32_b32 v36, -1, 0
	s_cbranch_scc1 .LBB0_66
	s_load_dwordx2 s[14:15], s[12:13], 0x8
	s_load_dwordx2 s[16:17], s[4:5], 0x0
	s_load_dwordx2 s[18:19], s[6:7], 0x100
	v_and_b32_e32 v1, 63, v1
	v_lshlrev_b32_e32 v2, 5, v1
	s_waitcnt lgkmcnt(0)
	s_cmp_lg_u64 s[14:15], 0
	v_mov_b32_e32 v3, 0
	s_cselect_b64 s[4:5], -1, 0
	v_lshl_add_u64 v[26:27], s[14:15], 0, v[2:3]
	s_mov_b64 s[12:13], 0x1800
	s_ashr_i32 s11, s10, 31
	v_lshl_add_u64 v[30:31], v[26:27], 0, s[12:13]
	s_lshl_b64 s[12:13], s[10:11], 13
	s_add_u32 s12, s16, s12
	s_addc_u32 s13, s17, s13
	s_mov_b64 s[6:7], 0x1000
	v_lshl_add_u64 v[4:5], s[12:13], 0, v[2:3]
	s_ashr_i32 s89, s88, 31
	v_lshl_add_u64 v[28:29], v[26:27], 0, s[6:7]
	v_lshl_add_u64 v[32:33], v[4:5], 0, s[6:7]
	s_lshl_b64 s[12:13], s[88:89], 13
	s_lshl_b64 s[6:7], s[10:11], 12
	s_add_u32 s6, s18, s6
	v_lshlrev_b32_e32 v2, 4, v1
	s_addc_u32 s7, s19, s7
	v_lshl_add_u64 v[2:3], s[6:7], 0, v[2:3]
	s_mov_b64 s[6:7], 0x14200000
	v_mbcnt_hi_u32_b32 v38, -1, v36
	v_lshl_add_u64 v[34:35], v[2:3], 0, s[6:7]
	v_cndmask_b32_e64 v1, 0, 1, s[4:5]
	v_and_b32_e32 v2, 64, v38
	s_lshl_b64 s[14:15], s[88:89], 12
	v_cmp_ne_u32_e64 s[4:5], 1, v1
	v_mov_b32_e32 v1, 0x358637bd
	s_mov_b32 s3, 0xf800000
	v_mov_b32_e32 v37, 0x260
	s_movk_i32 s11, 0x7fff
	s_mov_b32 s16, 0xffff0000
	v_add_u32_e32 v39, 64, v2
	v_xor_b32_e32 v40, 1, v38
	v_xor_b32_e32 v41, 2, v38
	v_xor_b32_e32 v42, 4, v38
	v_xor_b32_e32 v43, 8, v38
	v_xor_b32_e32 v44, 16, v38
	v_xor_b32_e32 v45, 32, v38
	s_and_b64 vcc, exec, s[4:5]
	s_cbranch_vccnz .Lrp_p0_nog
	global_load_dwordx4 v[100:103], v[26:27], off offset:2048
	global_load_dwordx4 v[104:107], v[26:27], off offset:2064
	global_load_dwordx4 v[108:111], v[28:29], off
	global_load_dwordx4 v[112:115], v[28:29], off offset:16
	global_load_dwordx4 v[116:119], v[30:31], off
	global_load_dwordx4 v[120:123], v[30:31], off offset:16
.Lrp_p0_nog:
	s_waitcnt vmcnt(0)
	s_branch .LBB0_64

.LBB0_64:
	s_and_b64 vcc, exec, s[4:5]
	s_cbranch_vccnz .LBB0_63
	global_load_dwordx4 v[18:21], v[32:33], off offset:-4096
	global_load_dwordx4 v[6:9], v[32:33], off offset:-2048
	global_load_dwordx4 v[2:5], v[32:33], off offset:16
	global_load_dwordx4 v[46:49], v[32:33], off offset:-4080
	global_load_dwordx4 v[22:25], v[32:33], off
	global_load_dwordx4 v[50:53], v[32:33], off offset:-2032
	global_load_dwordx4 v[14:17], v[32:33], off offset:2048
	global_load_dwordx4 v[10:13], v[32:33], off offset:2064
	global_load_dwordx4 v[54:57], v[26:27], off
	global_load_dwordx4 v[58:61], v[26:27], off offset:16
	v_cmp_lt_i32_e32 vcc, v40, v39
	s_waitcnt vmcnt(9)
	v_mov_b32_e32 v64, v19
	v_cndmask_b32_e32 v62, v38, v40, vcc
	v_mov_b32_e32 v68, v21
	s_waitcnt vmcnt(6)
	v_mov_b32_e32 v65, v47
	v_mov_b32_e32 v69, v49
	v_lshlrev_b32_e32 v85, 2, v62
	v_mov_b32_e32 v62, v18
	v_mov_b32_e32 v66, v20
	v_pk_mul_f32 v[70:71], v[8:9], v[8:9]
	v_pk_mul_f32 v[72:73], v[6:7], v[6:7]
	v_mov_b32_e32 v63, v46
	v_mov_b32_e32 v67, v48
	v_pk_mul_f32 v[64:65], v[64:65], v[64:65]
	v_pk_mul_f32 v[68:69], v[68:69], v[68:69]
	v_pk_mov_b32 v[86:87], v[72:73], v[70:71] op_sel:[1,0]
	v_mov_b32_e32 v73, v71
	v_pk_fma_f32 v[62:63], v[62:63], v[62:63], v[64:65]
	v_pk_fma_f32 v[64:65], v[66:67], v[66:67], v[68:69]
	v_pk_mul_f32 v[74:75], v[4:5], v[4:5]
	v_pk_mul_f32 v[76:77], v[2:3], v[2:3]
	s_waitcnt vmcnt(4)
	v_mul_f32_e32 v78, v51, v51
	v_mul_f32_e32 v80, v53, v53
	v_pk_add_f32 v[66:67], v[86:87], v[72:73]
	v_pk_add_f32 v[62:63], v[62:63], v[64:65]
	v_mul_f32_e32 v88, v24, v24
	v_mul_f32_e32 v89, v25, v25
	v_mul_f32_e32 v92, v23, v23
	v_mul_f32_e32 v93, v22, v22
	v_pk_mov_b32 v[70:71], v[76:77], v[74:75] op_sel:[1,0]
	v_mov_b32_e32 v77, v75
	v_pk_fma_f32 v[74:75], v[50:51], v[50:51], v[78:79] op_sel_hi:[1,1,0]
	v_pk_fma_f32 v[78:79], v[52:53], v[52:53], v[80:81] op_sel_hi:[1,1,0]
	v_pk_add_f32 v[66:67], v[66:67], v[66:67] op_sel:[0,1] op_sel_hi:[1,0]
	v_pk_add_f32 v[62:63], v[62:63], v[62:63] op_sel:[0,1] op_sel_hi:[1,0]
	v_mov_b32_e32 v75, v88
	v_mov_b32_e32 v79, v89
	v_mov_b32_e32 v67, v92
	v_mov_b32_e32 v63, v93
	v_pk_add_f32 v[64:65], v[74:75], v[78:79]
	v_pk_add_f32 v[62:63], v[62:63], v[66:67]
	s_waitcnt vmcnt(3)
	v_mul_f32_e32 v82, v15, v15
	v_mul_f32_e32 v84, v17, v17
	v_pk_add_f32 v[68:69], v[70:71], v[76:77]
	v_pk_add_f32 v[62:63], v[62:63], v[64:65]
	s_waitcnt vmcnt(2)
	v_mul_f32_e32 v90, v12, v12
	v_mul_f32_e32 v91, v13, v13
	v_mul_f32_e32 v94, v10, v10
	v_mul_f32_e32 v95, v11, v11
	v_pk_fma_f32 v[80:81], v[14:15], v[14:15], v[82:83] op_sel_hi:[1,1,0]
	v_pk_fma_f32 v[82:83], v[16:17], v[16:17], v[84:85] op_sel_hi:[1,1,0]
	v_pk_add_f32 v[68:69], v[68:69], v[68:69] op_sel:[0,1] op_sel_hi:[1,0]
	v_pk_add_f32 v[62:63], v[62:63], v[62:63] op_sel:[0,1] op_sel_hi:[1,0]
	v_mov_b32_e32 v81, v90
	v_mov_b32_e32 v83, v91
	v_mov_b32_e32 v69, v95
	v_mov_b32_e32 v63, v94
	v_pk_add_f32 v[70:71], v[80:81], v[82:83]
	v_pk_add_f32 v[62:63], v[62:63], v[68:69]
	v_cmp_lt_i32_e32 vcc, v41, v39
	v_pk_add_f32 v[62:63], v[62:63], v[70:71]
	s_waitcnt vmcnt(1)
	v_pk_mul_f32 v[18:19], v[18:19], v[54:55]
	v_add_f32_e32 v62, v62, v63
	ds_bpermute_b32 v63, v85, v62
	v_cndmask_b32_e32 v64, v38, v41, vcc
	v_lshlrev_b32_e32 v64, 2, v64
	v_cmp_lt_i32_e32 vcc, v42, v39
	v_pk_mul_f32 v[20:21], v[20:21], v[56:57]
	s_waitcnt lgkmcnt(0)
	v_add_f32_e32 v62, v62, v63
	ds_bpermute_b32 v63, v64, v62
	v_cndmask_b32_e32 v64, v38, v42, vcc
	v_lshlrev_b32_e32 v64, 2, v64
	v_cmp_lt_i32_e32 vcc, v43, v39
	s_waitcnt vmcnt(0)
	v_pk_mul_f32 v[46:47], v[46:47], v[58:59]
	s_waitcnt lgkmcnt(0)
	v_add_f32_e32 v62, v62, v63
	ds_bpermute_b32 v63, v64, v62
	v_cndmask_b32_e32 v64, v38, v43, vcc
	v_lshlrev_b32_e32 v64, 2, v64
	v_cmp_lt_i32_e32 vcc, v44, v39
	v_pk_mul_f32 v[48:49], v[48:49], v[60:61]
	s_waitcnt lgkmcnt(0)
	v_add_f32_e32 v62, v62, v63
	ds_bpermute_b32 v63, v64, v62
	v_cndmask_b32_e32 v64, v38, v44, vcc
	v_lshlrev_b32_e32 v64, 2, v64
	v_cmp_lt_i32_e32 vcc, v45, v39
	s_waitcnt lgkmcnt(0)
	v_add_f32_e32 v62, v62, v63
	ds_bpermute_b32 v63, v64, v62
	v_cndmask_b32_e32 v64, v38, v45, vcc
	v_lshlrev_b32_e32 v64, 2, v64
	s_waitcnt lgkmcnt(0)
	v_add_f32_e32 v62, v62, v63
	ds_bpermute_b32 v63, v64, v62
	s_waitcnt lgkmcnt(0)
	v_add_f32_e32 v62, v62, v63
	v_fmamk_f32 v62, v62, 0x3a000000, v1
	v_mul_f32_e32 v63, 0x4f800000, v62
	v_cmp_gt_f32_e32 vcc, s3, v62
	s_nop 1
	v_cndmask_b32_e32 v62, v62, v63, vcc
	v_sqrt_f32_e32 v63, v62
	s_nop 0
	v_add_u32_e32 v54, -1, v63
	v_add_u32_e32 v55, 1, v63
	v_fma_f32 v56, -v54, v63, v62
	v_fma_f32 v57, -v55, v63, v62
	v_cmp_ge_f32_e64 s[6:7], 0, v56
	s_nop 1
	v_cndmask_b32_e64 v54, v63, v54, s[6:7]
	v_cmp_lt_f32_e64 s[6:7], 0, v57
	s_nop 1
	v_cndmask_b32_e64 v54, v54, v55, s[6:7]
	v_mul_f32_e32 v55, 0x37800000, v54
	v_cndmask_b32_e32 v54, v54, v55, vcc
	v_cmp_class_f32_e32 vcc, v62, v37
	s_nop 1
	v_cndmask_b32_e32 v54, v54, v62, vcc
	v_div_scale_f32 v55, s[6:7], v54, v54, 1.0
	v_rcp_f32_e32 v56, v55
	v_div_scale_f32 v57, vcc, 1.0, v54, 1.0
	v_fma_f32 v58, -v55, v56, 1.0
	v_fmac_f32_e32 v56, v58, v56
	v_mul_f32_e32 v58, v57, v56
	v_fma_f32 v59, -v55, v58, v57
	v_fmac_f32_e32 v58, v59, v56
	v_fma_f32 v55, -v55, v58, v57
	v_div_fmas_f32 v55, v55, v56, v58
	v_div_fixup_f32 v54, v55, v54, 1.0
	v_pk_mul_f32 v[20:21], v[20:21], v[54:55] op_sel_hi:[1,0]
	v_pk_mul_f32 v[18:19], v[18:19], v[54:55] op_sel_hi:[1,0]
	v_pk_mul_f32 v[48:49], v[48:49], v[54:55] op_sel_hi:[1,0]
	v_pk_mul_f32 v[46:47], v[46:47], v[54:55] op_sel_hi:[1,0]
	v_bfe_u32 v55, v18, 16, 1
	v_bfe_u32 v57, v20, 16, 1
	v_bfe_u32 v59, v46, 16, 1
	v_bfe_u32 v61, v48, 16, 1
	v_bfe_u32 v56, v19, 16, 1
	v_bfe_u32 v58, v21, 16, 1
	v_bfe_u32 v60, v47, 16, 1
	v_bfe_u32 v62, v49, 16, 1
	v_add3_u32 v18, v18, v55, s11
	v_add3_u32 v20, v20, v57, s11
	v_add3_u32 v46, v46, v59, s11
	v_add3_u32 v48, v48, v61, s11
	v_add3_u32 v19, v19, v56, s11
	v_add3_u32 v21, v21, v58, s11
	v_add3_u32 v47, v47, v60, s11
	v_add3_u32 v49, v49, v62, s11
	v_lshrrev_b32_e32 v18, 16, v18
	v_lshrrev_b32_e32 v20, 16, v20
	v_lshrrev_b32_e32 v46, 16, v46
	v_lshrrev_b32_e32 v48, 16, v48
	v_and_or_b32 v18, v19, s16, v18
	v_and_or_b32 v19, v21, s16, v20
	v_and_or_b32 v20, v47, s16, v46
	v_and_or_b32 v21, v49, s16, v48
	global_store_dwordx4 v[34:35], v[18:21], off
	s_nop 1
	v_mov_b64_e32 v[18:19], v[100:101]
	v_mov_b64_e32 v[20:21], v[102:103]
	s_nop 0
	v_mov_b64_e32 v[46:47], v[104:105]
	v_mov_b64_e32 v[48:49], v[106:107]
	v_pk_mul_f32 v[8:9], v[8:9], v[20:21]
	v_pk_mul_f32 v[6:7], v[6:7], v[18:19]
	v_pk_mul_f32 v[18:19], v[52:53], v[48:49]
	v_pk_mul_f32 v[20:21], v[50:51], v[46:47]
	v_pk_mul_f32 v[8:9], v[8:9], v[54:55] op_sel_hi:[1,0]
	v_pk_mul_f32 v[6:7], v[6:7], v[54:55] op_sel_hi:[1,0]
	v_pk_mul_f32 v[18:19], v[18:19], v[54:55] op_sel_hi:[1,0]
	v_pk_mul_f32 v[20:21], v[20:21], v[54:55] op_sel_hi:[1,0]
	v_bfe_u32 v46, v6, 16, 1
	v_bfe_u32 v48, v8, 16, 1
	v_bfe_u32 v50, v20, 16, 1
	v_bfe_u32 v52, v18, 16, 1
	v_bfe_u32 v47, v7, 16, 1
	v_bfe_u32 v49, v9, 16, 1
	v_bfe_u32 v51, v21, 16, 1
	v_bfe_u32 v53, v19, 16, 1
	v_add3_u32 v6, v6, v46, s11
	v_add3_u32 v8, v8, v48, s11
	v_add3_u32 v20, v20, v50, s11
	v_add3_u32 v18, v18, v52, s11
	v_add3_u32 v7, v7, v47, s11
	v_add3_u32 v9, v9, v49, s11
	v_add3_u32 v21, v21, v51, s11
	v_add3_u32 v19, v19, v53, s11
	v_lshrrev_b32_e32 v6, 16, v6
	v_lshrrev_b32_e32 v8, 16, v8
	v_lshrrev_b32_e32 v20, 16, v20
	v_lshrrev_b32_e32 v18, 16, v18
	v_and_or_b32 v6, v7, s16, v6
	v_and_or_b32 v7, v9, s16, v8
	v_and_or_b32 v8, v21, s16, v20
	v_and_or_b32 v9, v19, s16, v18
	global_store_dwordx4 v[34:35], v[6:9], off offset:1024
	s_nop 1
	v_mov_b64_e32 v[6:7], v[108:109]
	v_mov_b64_e32 v[8:9], v[110:111]
	s_nop 0
	v_mov_b64_e32 v[18:19], v[112:113]
	v_mov_b64_e32 v[20:21], v[114:115]
	v_pk_mul_f32 v[8:9], v[24:25], v[8:9]
	v_pk_mul_f32 v[6:7], v[22:23], v[6:7]
	v_pk_mul_f32 v[4:5], v[4:5], v[20:21]
	v_pk_mul_f32 v[2:3], v[2:3], v[18:19]
	v_pk_mul_f32 v[8:9], v[8:9], v[54:55] op_sel_hi:[1,0]
	v_pk_mul_f32 v[6:7], v[6:7], v[54:55] op_sel_hi:[1,0]
	v_pk_mul_f32 v[4:5], v[54:55], v[4:5] op_sel_hi:[0,1]
	v_pk_mul_f32 v[2:3], v[54:55], v[2:3] op_sel_hi:[0,1]
	v_bfe_u32 v18, v6, 16, 1
	v_bfe_u32 v20, v8, 16, 1
	v_bfe_u32 v22, v2, 16, 1
	v_bfe_u32 v23, v3, 16, 1
	v_bfe_u32 v24, v4, 16, 1
	v_bfe_u32 v19, v7, 16, 1
	v_bfe_u32 v21, v9, 16, 1
	v_bfe_u32 v25, v5, 16, 1
	v_add3_u32 v6, v6, v18, s11
	v_add3_u32 v8, v8, v20, s11
	v_add3_u32 v2, v2, v22, s11
	v_add3_u32 v18, v3, v23, s11
	v_add3_u32 v3, v4, v24, s11
	v_add3_u32 v7, v7, v19, s11
	v_add3_u32 v9, v9, v21, s11
	v_add3_u32 v5, v5, v25, s11
	v_lshrrev_b32_e32 v4, 16, v6
	v_lshrrev_b32_e32 v6, 16, v8
	v_lshrrev_b32_e32 v8, 16, v2
	v_lshrrev_b32_e32 v19, 16, v3
	v_and_or_b32 v2, v7, s16, v4
	v_and_or_b32 v3, v9, s16, v6
	v_and_or_b32 v4, v18, s16, v8
	v_and_or_b32 v5, v5, s16, v19
	global_store_dwordx4 v[34:35], v[2:5], off offset:2048
	s_nop 1
	v_mov_b64_e32 v[2:3], v[116:117]
	v_mov_b64_e32 v[4:5], v[118:119]
	s_nop 0
	v_mov_b64_e32 v[6:7], v[120:121]
	v_mov_b64_e32 v[8:9], v[122:123]
	v_pk_mul_f32 v[4:5], v[16:17], v[4:5]
	v_pk_mul_f32 v[2:3], v[14:15], v[2:3]
	v_pk_mul_f32 v[8:9], v[12:13], v[8:9]
	v_pk_mul_f32 v[6:7], v[10:11], v[6:7]
	v_pk_mul_f32 v[4:5], v[54:55], v[4:5] op_sel_hi:[0,1]
	v_pk_mul_f32 v[2:3], v[54:55], v[2:3] op_sel_hi:[0,1]
	v_pk_mul_f32 v[8:9], v[54:55], v[8:9] op_sel_hi:[0,1]
	v_pk_mul_f32 v[6:7], v[54:55], v[6:7] op_sel_hi:[0,1]
	v_bfe_u32 v10, v2, 16, 1
	v_bfe_u32 v12, v4, 16, 1
	v_bfe_u32 v14, v6, 16, 1
	v_bfe_u32 v16, v8, 16, 1
	v_bfe_u32 v11, v3, 16, 1
	v_bfe_u32 v13, v5, 16, 1
	v_bfe_u32 v15, v7, 16, 1
	v_bfe_u32 v17, v9, 16, 1
	v_add3_u32 v2, v2, v10, s11
	v_add3_u32 v4, v4, v12, s11
	v_add3_u32 v6, v6, v14, s11
	v_add3_u32 v8, v8, v16, s11
	v_add3_u32 v3, v3, v11, s11
	v_add3_u32 v5, v5, v13, s11
	v_add3_u32 v7, v7, v15, s11
	v_add3_u32 v9, v9, v17, s11
	v_lshrrev_b32_e32 v2, 16, v2
	v_lshrrev_b32_e32 v4, 16, v4
	v_lshrrev_b32_e32 v6, 16, v6
	v_lshrrev_b32_e32 v8, 16, v8
	v_and_or_b32 v2, v3, s16, v2
	v_and_or_b32 v3, v5, s16, v4
	v_and_or_b32 v4, v7, s16, v6
	v_and_or_b32 v5, v9, s16, v8
	global_store_dwordx4 v[34:35], v[2:5], off offset:3072
	s_branch .LBB0_63

.LBB0_286:
	s_ashr_i32 s4, s4, 6
	s_add_i32 s8, s4, s81
	s_mov_b64 s[20:21], s[0:1]
	s_mov_b64 s[14:15], s[0:1]
	s_cmpk_gt_i32 s8, 0x1fff
	s_cbranch_scc1 .LBB0_293
	v_and_b32_e32 v1, 64, v223
	v_add_u32_e32 v1, 64, v1
	v_xor_b32_e32 v2, 1, v223
	v_cmp_lt_i32_e32 vcc, v2, v1
	s_load_dwordx2 s[4:5], s[10:11], 0x0
	s_load_dwordx2 s[22:23], s[20:21], 0xf8
	v_cndmask_b32_e32 v2, v223, v2, vcc
	v_lshlrev_b32_e32 v63, 2, v2
	v_xor_b32_e32 v2, 2, v223
	s_lshl_b64 s[10:11], s[72:73], 2
	v_cmp_lt_i32_e32 vcc, v2, v1
	s_waitcnt lgkmcnt(0)
	s_add_u32 s16, s16, s10
	s_addc_u32 s17, s17, s11
	v_cndmask_b32_e32 v2, v223, v2, vcc
	v_lshlrev_b32_e32 v80, 2, v2
	v_xor_b32_e32 v2, 4, v223
	v_and_b32_e32 v0, 63, v0
	s_cmp_lg_u64 s[22:23], 0
	v_cmp_lt_i32_e32 vcc, v2, v1
	s_load_dwordx2 s[20:21], s[14:15], 0x100
	s_cselect_b64 s[10:11], -1, 0
	s_cmp_lg_u64 s[18:19], 0
	v_lshlrev_b32_e32 v192, 5, v0
	v_cndmask_b32_e32 v2, v223, v2, vcc
	s_cselect_b64 s[14:15], -1, 0
	v_lshl_add_u64 v[40:41], s[16:17], 0, v[192:193]
	s_mov_b64 s[24:25], 0x1000
	v_lshl_add_u64 v[46:47], s[18:19], 0, v[192:193]
	v_lshlrev_b32_e32 v81, 2, v2
	v_xor_b32_e32 v2, 8, v223
	s_ashr_i32 s9, s8, 31
	v_lshl_add_u64 v[42:43], v[40:41], 0, s[24:25]
	s_mov_b64 s[16:17], 0x1800
	v_lshl_add_u64 v[48:49], v[46:47], 0, s[24:25]
	v_cmp_lt_i32_e32 vcc, v2, v1
	s_lshl_b64 s[24:25], s[8:9], 13
	v_lshl_add_u64 v[44:45], v[40:41], 0, s[16:17]
	v_lshl_add_u64 v[50:51], v[46:47], 0, s[16:17]
	v_cndmask_b32_e32 v2, v223, v2, vcc
	s_add_u32 s16, s4, s24
	v_lshlrev_b32_e32 v82, 2, v2
	v_xor_b32_e32 v2, 16, v223
	s_addc_u32 s17, s5, s25
	s_lshl_b64 s[4:5], s[8:9], 12
	v_cmp_lt_i32_e32 vcc, v2, v1
	s_waitcnt lgkmcnt(0)
	s_add_u32 s18, s20, s4
	s_addc_u32 s19, s21, s5
	v_cndmask_b32_e32 v2, v223, v2, vcc
	v_lshlrev_b32_e32 v83, 2, v2
	v_xor_b32_e32 v2, 32, v223
	s_add_u32 s20, s6, s4
	v_cmp_lt_i32_e32 vcc, v2, v1
	s_addc_u32 s21, s7, s5
	s_add_u32 s22, s22, s24
	v_cndmask_b32_e32 v1, v223, v2, vcc
	s_mov_b64 s[28:29], 0x1000
	s_mov_b64 s[26:27], 0x1800
	v_lshlrev_b32_e32 v84, 2, v1
	v_lshlrev_b32_e32 v52, 4, v0
	v_mov_b32_e32 v53, v193
	s_addc_u32 s23, s23, s25
	global_load_dwordx4 v[100:103], v[40:41], off offset:16
	global_load_dwordx4 v[104:107], v[40:41], off
	global_load_dwordx4 v[108:111], v[40:41], off offset:2064
	global_load_dwordx4 v[112:115], v[40:41], off offset:2048
	global_load_dwordx4 v[116:119], v[42:43], off offset:16
	global_load_dwordx4 v[120:123], v[42:43], off
	global_load_dwordx4 v[124:127], v[44:45], off offset:16
	global_load_dwordx4 v[128:131], v[44:45], off
	s_andn2_b64 vcc, exec, s[14:15]
	s_cbranch_vccnz .Lrp_a_nog
	global_load_dwordx4 v[132:135], v[46:47], off offset:16
	global_load_dwordx4 v[136:139], v[46:47], off
	global_load_dwordx4 v[140:143], v[46:47], off offset:2064
	global_load_dwordx4 v[144:147], v[46:47], off offset:2048
	global_load_dwordx4 v[148:151], v[48:49], off offset:16
	global_load_dwordx4 v[152:155], v[48:49], off
	global_load_dwordx4 v[156:159], v[50:51], off offset:16
	global_load_dwordx4 v[160:163], v[50:51], off

.LBB0_289:
	v_lshl_add_u64 v[0:1], s[16:17], 0, v[192:193]
	v_add_co_u32_e32 v4, vcc, 0x1000, v0
	v_lshl_add_u64 v[32:33], s[20:21], 0, v[52:53]
	s_nop 0
	v_addc_co_u32_e32 v5, vcc, 0, v1, vcc
	v_add_co_u32_e32 v34, vcc, 0x1ba00000, v32
	global_load_dwordx4 v[8:11], v[0:1], off offset:16
	global_load_dwordx4 v[12:15], v[0:1], off
	global_load_dwordx4 v[16:19], v[0:1], off offset:2064
	global_load_dwordx4 v[20:23], v[0:1], off offset:2048
	v_lshl_add_u64 v[2:3], v[0:1], 0, s[28:29]
	v_lshl_add_u64 v[0:1], v[0:1], 0, s[26:27]
	v_addc_co_u32_e32 v35, vcc, 0, v33, vcc
	global_load_dwordx4 v[28:31], v[4:5], off
	global_load_dwordx4 v[24:27], v[2:3], off offset:16
	s_nop 0
	global_load_dwordx4 v[4:7], v[4:5], off offset:2048
	s_nop 0
	global_load_dwordx4 v[0:3], v[0:1], off offset:16
	s_nop 0
	global_load_dwordx4 v[64:67], v[34:35], off
	global_load_dwordx4 v[68:71], v[34:35], off offset:1024
	global_load_dwordx4 v[58:61], v[34:35], off offset:2048
	global_load_dwordx4 v[88:91], v[34:35], off offset:3072
	s_mov_b32 s4, 0xf800000
	s_waitcnt vmcnt(3)
	v_and_b32_e32 v75, 0xffff0000, v66
	v_and_b32_e32 v74, 0xffff0000, v64
	v_and_b32_e32 v79, 0xffff0000, v67
	v_and_b32_e32 v78, 0xffff0000, v65
	v_lshlrev_b32_e32 v73, 16, v66
	v_lshlrev_b32_e32 v72, 16, v64
	v_lshlrev_b32_e32 v77, 16, v67
	v_lshlrev_b32_e32 v76, 16, v65
	v_pk_mul_f32 v[34:35], v[74:75], v[74:75]
	v_pk_mul_f32 v[64:65], v[78:79], v[78:79]
	v_pk_fma_f32 v[34:35], v[72:73], v[72:73], v[34:35]
	v_pk_fma_f32 v[64:65], v[76:77], v[76:77], v[64:65]
	s_waitcnt vmcnt(2)
	v_lshlrev_b32_e32 v32, 16, v70
	v_pk_add_f32 v[34:35], v[34:35], v[64:65]
	v_and_b32_e32 v33, 0xffff0000, v70
	v_pk_add_f32 v[64:65], v[34:35], v[34:35] op_sel_hi:[0,1]
	v_lshlrev_b32_e32 v35, 16, v69
	v_lshlrev_b32_e32 v34, 16, v68
	v_and_b32_e32 v69, 0xffff0000, v69
	v_and_b32_e32 v68, 0xffff0000, v68
	s_waitcnt vmcnt(1)
	v_lshlrev_b32_e32 v36, 16, v58
	v_pk_mul_f32 v[66:67], v[68:69], v[68:69]
	v_lshlrev_b32_e32 v70, 16, v71
	s_waitcnt vmcnt(0)
	v_lshlrev_b32_e32 v56, 16, v90
	v_and_b32_e32 v85, 0xffff0000, v90
	v_lshlrev_b32_e32 v54, 16, v91
	v_and_b32_e32 v55, 0xffff0000, v91
	v_pk_fma_f32 v[66:67], v[34:35], v[34:35], v[66:67]
	v_mul_f32_e32 v37, v32, v32
	v_mul_f32_e32 v91, v33, v33
	v_and_b32_e32 v71, 0xffff0000, v71
	v_mul_f32_e32 v62, v70, v70
	v_mov_b32_e32 v90, v36
	v_and_b32_e32 v86, 0xffff0000, v58
	v_lshlrev_b32_e32 v38, 16, v59
	v_and_b32_e32 v39, 0xffff0000, v59
	v_pk_add_f32 v[66:67], v[66:67], v[66:67] op_sel_hi:[0,1]
	v_pk_fma_f32 v[92:93], v[70:71], v[70:71], v[62:63] op_sel_hi:[1,1,0]
	v_pk_add_f32 v[90:91], v[36:37], v[90:91]
	v_mul_f32_e32 v92, v86, v86
	v_mul_f32_e32 v64, v38, v38
	v_mul_f32_e32 v66, v39, v39
	v_mul_f32_e32 v94, v36, v36
	v_mov_b32_e32 v95, v91
	v_pk_add_f32 v[90:91], v[94:95], v[92:93]
	v_pk_add_f32 v[64:65], v[64:65], v[66:67]
	v_and_b32_e32 v67, 0xffff0000, v61
	v_pk_add_f32 v[64:65], v[90:91], v[64:65]
	v_and_b32_e32 v66, 0xffff0000, v60
	v_pk_add_f32 v[90:91], v[64:65], v[64:65] op_sel_hi:[0,1]
	v_lshlrev_b32_e32 v65, 16, v61
	v_lshlrev_b32_e32 v64, 16, v60
	v_pk_mul_f32 v[60:61], v[66:67], v[66:67]
	v_lshlrev_b32_e32 v58, 16, v88
	v_pk_fma_f32 v[60:61], v[64:65], v[64:65], v[60:61]
	v_and_b32_e32 v59, 0xffff0000, v88
	v_pk_add_f32 v[92:93], v[60:61], v[60:61] op_sel_hi:[0,1]
	v_lshlrev_b32_e32 v60, 16, v89
	v_mul_f32_e32 v57, v58, v58
	v_mul_f32_e32 v95, v59, v59
	v_and_b32_e32 v61, 0xffff0000, v89
	v_mul_f32_e32 v62, v60, v60
	v_mov_b32_e32 v94, v56
	v_pk_fma_f32 v[88:89], v[60:61], v[60:61], v[62:63] op_sel_hi:[1,1,0]
	v_pk_add_f32 v[94:95], v[56:57], v[94:95]
	v_mul_f32_e32 v88, v85, v85
	v_mul_f32_e32 v92, v54, v54
	v_mul_f32_e32 v90, v55, v55
	v_mul_f32_e32 v96, v56, v56
	v_mov_b32_e32 v97, v95
	v_pk_add_f32 v[88:89], v[96:97], v[88:89]
	v_pk_add_f32 v[90:91], v[92:93], v[90:91]
	v_mov_b32_e32 v96, v72
	v_pk_add_f32 v[88:89], v[88:89], v[90:91]
	v_mov_b32_e32 v97, v74
	v_add_f32_e32 v37, v88, v89
	ds_bpermute_b32 v57, v63, v37
	v_mov_b32_e32 v74, v73
	s_waitcnt lgkmcnt(0)
	v_add_f32_e32 v37, v37, v57
	ds_bpermute_b32 v57, v80, v37
	s_waitcnt lgkmcnt(0)
	v_add_f32_e32 v37, v37, v57
	ds_bpermute_b32 v57, v81, v37
	s_waitcnt lgkmcnt(0)
	v_add_f32_e32 v37, v37, v57
	ds_bpermute_b32 v57, v82, v37
	s_waitcnt lgkmcnt(0)
	v_add_f32_e32 v37, v37, v57
	ds_bpermute_b32 v57, v83, v37
	s_waitcnt lgkmcnt(0)
	v_add_f32_e32 v37, v37, v57
	ds_bpermute_b32 v57, v84, v37
	s_waitcnt lgkmcnt(0)
	v_add_f32_e32 v37, v37, v57
	v_fmamk_f32 v37, v37, 0x3a000000, v219
	v_cmp_gt_f32_e32 vcc, s4, v37
	v_mul_f32_e32 v57, 0x4f800000, v37
	s_nop 0
	v_cndmask_b32_e32 v37, v37, v57, vcc
	v_sqrt_f32_e32 v57, v37
	s_nop 0
	v_add_u32_e32 v62, -1, v57
	v_fma_f32 v87, -v62, v57, v37
	v_cmp_ge_f32_e64 s[6:7], 0, v87
	v_add_u32_e32 v87, 1, v57
	s_nop 0
	v_cndmask_b32_e64 v62, v57, v62, s[6:7]
	v_fma_f32 v57, -v87, v57, v37
	v_cmp_lt_f32_e64 s[6:7], 0, v57
	s_nop 1
	v_cndmask_b32_e64 v57, v62, v87, s[6:7]
	v_mul_f32_e32 v62, 0x37800000, v57
	v_cndmask_b32_e32 v57, v57, v62, vcc
	v_cmp_class_f32_e32 vcc, v37, v220
	s_nop 1
	v_cndmask_b32_e32 v37, v57, v37, vcc
	v_div_scale_f32 v57, s[4:5], v37, v37, 0.5
	v_rcp_f32_e32 v62, v57
	s_nop 0
	v_fma_f32 v87, -v57, v62, 1.0
	v_fmac_f32_e32 v62, v87, v62
	v_div_scale_f32 v87, vcc, 0.5, v37, 0.5
	v_mul_f32_e32 v88, v87, v62
	v_fma_f32 v89, -v57, v88, v87
	v_fmac_f32_e32 v88, v89, v62
	v_fma_f32 v57, -v57, v88, v87
	v_div_fmas_f32 v57, v57, v62, v88
	v_mov_b64_e32 v[88:89], v[100:101]
	v_mov_b64_e32 v[90:91], v[102:103]
	v_mov_b64_e32 v[92:93], v[104:105]
	v_mov_b64_e32 v[94:95], v[106:107]
	v_div_fixup_f32 v62, v57, v37, 0.5
	v_mov_b32_e32 v37, v86
	v_mov_b32_e32 v57, v85
	s_andn2_b64 vcc, exec, s[10:11]
	v_pk_mul_f32 v[72:73], v[88:89], v[74:75]
	v_pk_mul_f32 v[92:93], v[92:93], v[96:97]
	v_mov_b32_e32 v97, v78
	v_mov_b32_e32 v78, v77
	v_pk_mul_f32 v[74:75], v[90:91], v[78:79]
	v_mov_b32_e32 v96, v76
	v_pk_fma_f32 v[10:11], v[74:75], v[62:63], v[10:11] op_sel_hi:[1,0,1]
	v_pk_fma_f32 v[8:9], v[72:73], v[62:63], v[8:9] op_sel_hi:[1,0,1]
	v_mov_b64_e32 v[72:73], v[108:109]
	v_mov_b64_e32 v[74:75], v[110:111]
	v_mov_b64_e32 v[76:77], v[112:113]
	v_mov_b64_e32 v[78:79], v[114:115]
	v_mov_b32_e32 v89, v68
	v_mov_b32_e32 v68, v35
	v_mov_b32_e32 v88, v34
	v_pk_mul_f32 v[94:95], v[94:95], v[96:97]
	v_pk_fma_f32 v[12:13], v[92:93], v[62:63], v[12:13] op_sel_hi:[1,0,1]
	v_pk_fma_f32 v[14:15], v[94:95], v[62:63], v[14:15] op_sel_hi:[1,0,1]
	v_pk_mul_f32 v[32:33], v[72:73], v[32:33]
	v_pk_mul_f32 v[34:35], v[78:79], v[68:69]
	v_pk_fma_f32 v[16:17], v[32:33], v[62:63], v[16:17] op_sel_hi:[1,0,1]
	v_pk_fma_f32 v[22:23], v[34:35], v[62:63], v[22:23] op_sel_hi:[1,0,1]
	v_pk_mul_f32 v[34:35], v[74:75], v[70:71]
	v_pk_mul_f32 v[76:77], v[76:77], v[88:89]
	v_pk_fma_f32 v[18:19], v[34:35], v[62:63], v[18:19] op_sel_hi:[1,0,1]
	v_mov_b64_e32 v[32:33], v[116:117]
	v_mov_b64_e32 v[34:35], v[118:119]
	v_mov_b64_e32 v[68:69], v[120:121]
	v_mov_b64_e32 v[70:71], v[122:123]
	v_pk_fma_f32 v[20:21], v[76:77], v[62:63], v[20:21] op_sel_hi:[1,0,1]
	v_pk_mul_f32 v[36:37], v[68:69], v[36:37]
	s_nop 0
	v_pk_fma_f32 v[28:29], v[36:37], v[62:63], v[28:29] op_sel_hi:[1,0,1]
	v_mov_b32_e32 v36, v64
	v_mov_b32_e32 v37, v66
	v_mov_b32_e32 v66, v65
	v_pk_mul_f32 v[38:39], v[70:71], v[38:39]
	v_pk_mul_f32 v[32:33], v[32:33], v[36:37]
	v_pk_mul_f32 v[34:35], v[34:35], v[66:67]
	v_pk_fma_f32 v[30:31], v[38:39], v[62:63], v[30:31] op_sel_hi:[1,0,1]
	v_pk_fma_f32 v[26:27], v[34:35], v[62:63], v[26:27] op_sel_hi:[1,0,1]
	v_pk_fma_f32 v[24:25], v[32:33], v[62:63], v[24:25] op_sel_hi:[1,0,1]
	v_mov_b64_e32 v[32:33], v[124:125]
	v_mov_b64_e32 v[34:35], v[126:127]
	v_mov_b64_e32 v[36:37], v[128:129]
	v_mov_b64_e32 v[38:39], v[130:131]
	v_pk_mul_f32 v[32:33], v[32:33], v[56:57]
	v_pk_mul_f32 v[36:37], v[36:37], v[58:59]
	v_pk_mul_f32 v[38:39], v[38:39], v[60:61]
	v_pk_mul_f32 v[34:35], v[34:35], v[54:55]
	v_pk_fma_f32 v[6:7], v[38:39], v[62:63], v[6:7] op_sel_hi:[1,0,1]
	v_pk_fma_f32 v[4:5], v[36:37], v[62:63], v[4:5] op_sel_hi:[1,0,1]
	v_pk_fma_f32 v[2:3], v[34:35], v[62:63], v[2:3] op_sel_hi:[1,0,1]
	v_pk_fma_f32 v[0:1], v[32:33], v[62:63], v[0:1] op_sel_hi:[1,0,1]
	s_cbranch_vccnz .LBB0_291
	v_lshl_add_u64 v[32:33], s[22:23], 0, v[192:193]
	global_store_dwordx4 v[32:33], v[12:15], off
	global_store_dwordx4 v[32:33], v[8:11], off offset:16
	global_store_dwordx4 v[32:33], v[20:23], off offset:2048
	global_store_dwordx4 v[32:33], v[16:19], off offset:2064
	v_add_co_u32_e32 v32, vcc, 0x1000, v32
	s_nop 1
	v_addc_co_u32_e32 v33, vcc, 0, v33, vcc
	global_store_dwordx4 v[32:33], v[28:31], off
	global_store_dwordx4 v[32:33], v[24:27], off offset:16
	global_store_dwordx4 v[32:33], v[4:7], off offset:2048
	global_store_dwordx4 v[32:33], v[0:3], off offset:2064
.LBB0_291:
	s_andn2_b64 vcc, exec, s[14:15]
	s_cbranch_vccnz .LBB0_288
	v_mov_b32_e32 v34, v13
	v_mov_b32_e32 v35, v9
	v_mov_b32_e32 v32, v12
	v_mov_b32_e32 v33, v8
	v_pk_mul_f32 v[34:35], v[34:35], v[34:35]
	v_mov_b32_e32 v36, v15
	v_mov_b32_e32 v37, v11
	v_pk_fma_f32 v[32:33], v[32:33], v[32:33], v[34:35]
	v_mov_b32_e32 v34, v14
	v_mov_b32_e32 v35, v10
	v_pk_mul_f32 v[36:37], v[36:37], v[36:37]
	s_mov_b32 s4, 0xf800000
	v_pk_fma_f32 v[34:35], v[34:35], v[34:35], v[36:37]
	v_pk_mul_f32 v[36:37], v[20:21], v[20:21]
	v_pk_add_f32 v[32:33], v[32:33], v[34:35]
	v_pk_mul_f32 v[34:35], v[22:23], v[22:23]
	v_pk_add_f32 v[32:33], v[32:33], v[32:33] op_sel_hi:[0,1]
	v_pk_mov_b32 v[38:39], v[36:37], v[34:35] op_sel:[1,0]
	v_mov_b32_e32 v37, v35
	v_mul_f32_e32 v32, v16, v16
	v_pk_add_f32 v[34:35], v[38:39], v[36:37]
	v_pk_fma_f32 v[36:37], v[16:17], v[16:17], v[32:33] op_sel_hi:[1,1,0]
	v_mul_f32_e32 v32, v18, v18
	v_pk_add_f32 v[34:35], v[34:35], v[34:35] op_sel_hi:[0,1]
	v_pk_fma_f32 v[38:39], v[18:19], v[18:19], v[32:33] op_sel_hi:[1,1,0]
	v_mul_f32_e32 v36, v28, v28
	v_mul_f32_e32 v38, v29, v29
	v_mul_f32_e32 v34, v30, v30
	v_mul_f32_e32 v32, v31, v31
	v_pk_add_f32 v[36:37], v[36:37], v[38:39]
	v_pk_add_f32 v[32:33], v[34:35], v[32:33]
	v_pk_mul_f32 v[34:35], v[26:27], v[26:27]
	v_pk_add_f32 v[32:33], v[36:37], v[32:33]
	v_pk_mul_f32 v[36:37], v[24:25], v[24:25]
	v_pk_add_f32 v[32:33], v[32:33], v[32:33] op_sel_hi:[0,1]
	v_pk_mov_b32 v[38:39], v[36:37], v[34:35] op_sel:[1,0]
	v_mov_b32_e32 v37, v35
	v_mul_f32_e32 v32, v4, v4
	v_pk_add_f32 v[34:35], v[38:39], v[36:37]
	v_pk_fma_f32 v[36:37], v[4:5], v[4:5], v[32:33] op_sel_hi:[1,1,0]
	v_mul_f32_e32 v32, v6, v6
	v_pk_add_f32 v[34:35], v[34:35], v[34:35] op_sel_hi:[0,1]
	v_pk_fma_f32 v[38:39], v[6:7], v[6:7], v[32:33] op_sel_hi:[1,1,0]
	v_mul_f32_e32 v36, v0, v0
	v_mul_f32_e32 v38, v1, v1
	v_mul_f32_e32 v34, v2, v2
	v_mul_f32_e32 v32, v3, v3
	v_pk_add_f32 v[36:37], v[36:37], v[38:39]
	v_pk_add_f32 v[32:33], v[34:35], v[32:33]
	v_lshl_add_u64 v[38:39], s[18:19], 0, v[52:53]
	v_pk_add_f32 v[32:33], v[36:37], v[32:33]
	s_nop 0
	v_add_f32_e32 v32, v32, v33
	ds_bpermute_b32 v33, v63, v32
	s_waitcnt lgkmcnt(0)
	v_add_f32_e32 v32, v32, v33
	ds_bpermute_b32 v33, v80, v32
	s_waitcnt lgkmcnt(0)
	v_add_f32_e32 v32, v32, v33
	ds_bpermute_b32 v33, v81, v32
	s_waitcnt lgkmcnt(0)
	v_add_f32_e32 v32, v32, v33
	ds_bpermute_b32 v33, v82, v32
	s_waitcnt lgkmcnt(0)
	v_add_f32_e32 v32, v32, v33
	ds_bpermute_b32 v33, v83, v32
	s_waitcnt lgkmcnt(0)
	v_add_f32_e32 v32, v32, v33
	ds_bpermute_b32 v33, v84, v32
	s_waitcnt lgkmcnt(0)
	v_add_f32_e32 v32, v32, v33
	v_fmamk_f32 v32, v32, 0x3a000000, v219
	v_cmp_gt_f32_e32 vcc, s4, v32
	v_mul_f32_e32 v33, 0x4f800000, v32
	s_nop 0
	v_cndmask_b32_e32 v32, v32, v33, vcc
	v_sqrt_f32_e32 v33, v32
	s_nop 0
	v_add_u32_e32 v34, -1, v33
	v_fma_f32 v35, -v34, v33, v32
	v_cmp_ge_f32_e64 s[6:7], 0, v35
	v_add_u32_e32 v35, 1, v33
	s_nop 0
	v_cndmask_b32_e64 v34, v33, v34, s[6:7]
	v_fma_f32 v33, -v35, v33, v32
	v_cmp_lt_f32_e64 s[6:7], 0, v33
	s_nop 1
	v_cndmask_b32_e64 v33, v34, v35, s[6:7]
	v_mul_f32_e32 v34, 0x37800000, v33
	v_cndmask_b32_e32 v33, v33, v34, vcc
	v_cmp_class_f32_e32 vcc, v32, v220
	s_nop 1
	v_cndmask_b32_e32 v32, v33, v32, vcc
	v_div_scale_f32 v33, s[4:5], v32, v32, 1.0
	v_rcp_f32_e32 v34, v33
	s_mov_b32 s4, 0xffff0000
	s_mov_b32 s5, 0x14200000
	v_fma_f32 v35, -v33, v34, 1.0
	v_fmac_f32_e32 v34, v35, v34
	v_div_scale_f32 v35, vcc, 1.0, v32, 1.0
	v_mul_f32_e32 v36, v35, v34
	v_fma_f32 v37, -v33, v36, v35
	v_fmac_f32_e32 v36, v37, v34
	v_fma_f32 v33, -v33, v36, v35
	v_div_fmas_f32 v33, v33, v34, v36
	v_div_fixup_f32 v36, v33, v32, 1.0
	v_mov_b64_e32 v[32:33], v[132:133]
	v_mov_b64_e32 v[34:35], v[134:135]
	v_mov_b64_e32 v[54:55], v[136:137]
	v_mov_b64_e32 v[56:57], v[138:139]
	v_pk_mul_f32 v[10:11], v[10:11], v[34:35]
	v_pk_mul_f32 v[12:13], v[12:13], v[54:55]
	v_pk_mul_f32 v[8:9], v[8:9], v[32:33]
	v_pk_mul_f32 v[12:13], v[12:13], v[36:37] op_sel_hi:[1,0]
	v_pk_mul_f32 v[32:33], v[10:11], v[36:37] op_sel_hi:[1,0]
	v_bfe_u32 v10, v12, 16, 1
	v_pk_mul_f32 v[14:15], v[14:15], v[56:57]
	v_add3_u32 v10, v12, v10, s77
	v_bfe_u32 v11, v13, 16, 1
	v_pk_mul_f32 v[14:15], v[14:15], v[36:37] op_sel_hi:[1,0]
	v_lshrrev_b32_e32 v10, 16, v10
	v_add3_u32 v11, v13, v11, s77
	v_and_or_b32 v10, v11, s4, v10
	v_bfe_u32 v11, v14, 16, 1
	v_add3_u32 v11, v14, v11, s77
	v_bfe_u32 v12, v15, 16, 1
	v_pk_mul_f32 v[8:9], v[8:9], v[36:37] op_sel_hi:[1,0]
	v_lshrrev_b32_e32 v11, 16, v11
	v_add3_u32 v12, v15, v12, s77
	v_and_or_b32 v11, v12, s4, v11
	v_bfe_u32 v12, v8, 16, 1
	v_add3_u32 v8, v8, v12, s77
	v_bfe_u32 v12, v9, 16, 1
	v_lshrrev_b32_e32 v8, 16, v8
	v_add3_u32 v9, v9, v12, s77
	v_and_or_b32 v12, v9, s4, v8
	v_bfe_u32 v8, v32, 16, 1
	v_add3_u32 v8, v32, v8, s77
	v_bfe_u32 v9, v33, 16, 1
	v_lshrrev_b32_e32 v8, 16, v8
	v_add3_u32 v9, v33, v9, s77
	v_and_or_b32 v13, v9, s4, v8
	v_add_co_u32_e32 v8, vcc, s5, v38
	s_nop 1
	v_addc_co_u32_e32 v9, vcc, 0, v39, vcc
	global_store_dwordx4 v[8:9], v[10:13], off
	s_nop 1
	v_mov_b64_e32 v[10:11], v[140:141]
	v_mov_b64_e32 v[12:13], v[142:143]
	s_nop 0
	v_mov_b64_e32 v[32:33], v[144:145]
	v_mov_b64_e32 v[34:35], v[146:147]
	v_pk_mul_f32 v[12:13], v[18:19], v[12:13]
	v_pk_mul_f32 v[20:21], v[20:21], v[32:33]
	v_pk_mul_f32 v[10:11], v[16:17], v[10:11]
	v_pk_mul_f32 v[20:21], v[20:21], v[36:37] op_sel_hi:[1,0]
	v_pk_mul_f32 v[16:17], v[12:13], v[36:37] op_sel_hi:[1,0]
	v_pk_mul_f32 v[12:13], v[10:11], v[36:37] op_sel_hi:[1,0]
	v_bfe_u32 v10, v20, 16, 1
	v_pk_mul_f32 v[14:15], v[22:23], v[34:35]
	v_add3_u32 v10, v20, v10, s77
	v_bfe_u32 v11, v21, 16, 1
	v_pk_mul_f32 v[14:15], v[14:15], v[36:37] op_sel_hi:[1,0]
	v_lshrrev_b32_e32 v10, 16, v10
	v_add3_u32 v11, v21, v11, s77
	v_and_or_b32 v10, v11, s4, v10
	v_bfe_u32 v11, v14, 16, 1
	v_add3_u32 v11, v14, v11, s77
	v_bfe_u32 v14, v15, 16, 1
	v_lshrrev_b32_e32 v11, 16, v11
	v_add3_u32 v14, v15, v14, s77
	v_and_or_b32 v11, v14, s4, v11
	v_bfe_u32 v14, v12, 16, 1
	v_add3_u32 v12, v12, v14, s77
	v_bfe_u32 v14, v13, 16, 1
	v_lshrrev_b32_e32 v12, 16, v12
	v_add3_u32 v13, v13, v14, s77
	v_and_or_b32 v12, v13, s4, v12
	v_bfe_u32 v13, v16, 16, 1
	v_add3_u32 v13, v16, v13, s77
	v_bfe_u32 v14, v17, 16, 1
	v_lshrrev_b32_e32 v13, 16, v13
	v_add3_u32 v14, v17, v14, s77
	v_and_or_b32 v13, v14, s4, v13
	global_store_dwordx4 v[8:9], v[10:13], off offset:1024
	s_nop 1
	v_mov_b64_e32 v[10:11], v[148:149]
	v_mov_b64_e32 v[12:13], v[150:151]
	s_nop 0
	v_mov_b64_e32 v[14:15], v[152:153]
	v_mov_b64_e32 v[16:17], v[154:155]
	v_pk_mul_f32 v[12:13], v[26:27], v[12:13]
	v_pk_mul_f32 v[14:15], v[28:29], v[14:15]
	v_pk_mul_f32 v[10:11], v[24:25], v[10:11]
	v_pk_mul_f32 v[14:15], v[36:37], v[14:15] op_sel_hi:[0,1]
	v_pk_mul_f32 v[18:19], v[36:37], v[12:13] op_sel_hi:[0,1]
	v_pk_mul_f32 v[12:13], v[36:37], v[10:11] op_sel_hi:[0,1]
	v_bfe_u32 v10, v14, 16, 1
	v_pk_mul_f32 v[16:17], v[30:31], v[16:17]
	v_add3_u32 v10, v14, v10, s77
	v_bfe_u32 v11, v15, 16, 1
	v_pk_mul_f32 v[16:17], v[36:37], v[16:17] op_sel_hi:[0,1]
	v_lshrrev_b32_e32 v10, 16, v10
	v_add3_u32 v11, v15, v11, s77
	v_and_or_b32 v10, v11, s4, v10
	v_bfe_u32 v11, v16, 16, 1
	v_add3_u32 v11, v16, v11, s77
	v_bfe_u32 v14, v17, 16, 1
	v_lshrrev_b32_e32 v11, 16, v11
	v_add3_u32 v14, v17, v14, s77
	v_and_or_b32 v11, v14, s4, v11
	v_bfe_u32 v14, v12, 16, 1
	v_add3_u32 v12, v12, v14, s77
	v_bfe_u32 v14, v13, 16, 1
	v_lshrrev_b32_e32 v12, 16, v12
	v_add3_u32 v13, v13, v14, s77
	v_and_or_b32 v12, v13, s4, v12
	v_bfe_u32 v13, v18, 16, 1
	v_add3_u32 v13, v18, v13, s77
	v_bfe_u32 v14, v19, 16, 1
	v_lshrrev_b32_e32 v13, 16, v13
	v_add3_u32 v14, v19, v14, s77
	v_and_or_b32 v13, v14, s4, v13
	global_store_dwordx4 v[8:9], v[10:13], off offset:2048
	s_nop 1
	v_mov_b64_e32 v[10:11], v[156:157]
	v_mov_b64_e32 v[12:13], v[158:159]
	s_nop 0
	v_mov_b64_e32 v[14:15], v[160:161]
	v_mov_b64_e32 v[16:17], v[162:163]
	v_pk_mul_f32 v[2:3], v[2:3], v[12:13]
	v_pk_mul_f32 v[4:5], v[4:5], v[14:15]
	v_pk_mul_f32 v[0:1], v[0:1], v[10:11]
	v_pk_mul_f32 v[4:5], v[36:37], v[4:5] op_sel_hi:[0,1]
	v_pk_mul_f32 v[10:11], v[36:37], v[2:3] op_sel_hi:[0,1]
	v_pk_mul_f32 v[2:3], v[36:37], v[0:1] op_sel_hi:[0,1]
	v_bfe_u32 v0, v4, 16, 1
	v_pk_mul_f32 v[6:7], v[6:7], v[16:17]
	v_add3_u32 v0, v4, v0, s77
	v_bfe_u32 v1, v5, 16, 1
	v_pk_mul_f32 v[6:7], v[36:37], v[6:7] op_sel_hi:[0,1]
	v_lshrrev_b32_e32 v0, 16, v0
	v_add3_u32 v1, v5, v1, s77
	v_and_or_b32 v0, v1, s4, v0
	v_bfe_u32 v1, v6, 16, 1
	v_add3_u32 v1, v6, v1, s77
	v_bfe_u32 v4, v7, 16, 1
	v_lshrrev_b32_e32 v1, 16, v1
	v_add3_u32 v4, v7, v4, s77
	v_and_or_b32 v1, v4, s4, v1
	v_bfe_u32 v4, v2, 16, 1
	v_add3_u32 v2, v2, v4, s77
	v_bfe_u32 v4, v3, 16, 1
	v_lshrrev_b32_e32 v2, 16, v2
	v_add3_u32 v3, v3, v4, s77
	v_and_or_b32 v2, v3, s4, v2
	v_bfe_u32 v3, v10, 16, 1
	v_add3_u32 v3, v10, v3, s77
	v_bfe_u32 v4, v11, 16, 1
	v_lshrrev_b32_e32 v3, 16, v3
	v_add3_u32 v4, v11, v4, s77
	v_and_or_b32 v3, v4, s4, v3
	global_store_dwordx4 v[8:9], v[0:3], off offset:3072
	s_branch .LBB0_288

.LBB0_743:
	s_or_b64 exec, exec, s[4:5]
	s_waitcnt lgkmcnt(0)
	v_mov_b32_e32 v0, v214
	s_barrier
	s_mov_b64 s[10:11], s[0:1]
	v_readfirstlane_b32 s4, v0
	s_ashr_i32 s4, s4, 6
	s_add_i32 s6, s4, s81
	s_mov_b64 s[12:13], s[0:1]
	s_mov_b64 s[4:5], s[0:1]
	s_mov_b64 s[8:9], s[0:1]
	s_mov_b64 s[14:15], s[0:1]
	s_mov_b64 s[16:17], s[0:1]
	s_cmpk_gt_i32 s6, 0x1fff
	s_cbranch_scc1 .LBB0_750
	s_load_dwordx2 s[18:19], s[10:11], 0x100
	s_nop 0
	s_load_dwordx2 s[12:13], s[12:13], 0xf8
	s_nop 0
	s_load_dwordx2 s[10:11], s[16:17], 0xd0
	s_nop 0
	s_load_dwordx2 s[4:5], s[4:5], 0xf8
	s_nop 0
	s_load_dwordx2 s[14:15], s[14:15], 0xc8
	s_nop 0
	s_load_dwordx2 s[16:17], s[8:9], 0x100
	s_lshl_b64 s[8:9], s[72:73], 2
	s_waitcnt lgkmcnt(0)
	s_add_u32 s20, s10, s8
	s_addc_u32 s21, s11, s9
	s_add_u32 s14, s14, s8
	s_addc_u32 s15, s15, s9
	s_cmp_lg_u64 s[4:5], 0
	v_and_b32_e32 v0, 63, v0
	s_cselect_b64 s[8:9], -1, 0
	s_cmp_lg_u64 s[10:11], 0
	s_cselect_b64 s[10:11], -1, 0
	v_lshlrev_b32_e32 v192, 5, v0
	s_ashr_i32 s7, s6, 31
	v_lshl_add_u64 v[46:47], s[20:21], 0, v[192:193]
	s_lshl_b64 s[20:21], s[6:7], 13
	v_lshl_add_u64 v[40:41], s[14:15], 0, v[192:193]
	s_mov_b64 s[22:23], 0x1000
	s_add_u32 s12, s12, s20
	v_lshl_add_u64 v[42:43], v[40:41], 0, s[22:23]
	s_mov_b64 s[14:15], 0x1800
	v_lshl_add_u64 v[48:49], v[46:47], 0, s[22:23]
	s_addc_u32 s13, s13, s21
	s_lshl_b64 s[22:23], s[6:7], 12
	v_lshl_add_u64 v[44:45], v[40:41], 0, s[14:15]
	v_lshl_add_u64 v[50:51], v[46:47], 0, s[14:15]
	s_add_u32 s14, s16, s22
	s_addc_u32 s15, s17, s23
	s_add_u32 s16, s18, s22
	s_addc_u32 s17, s19, s23
	s_add_u32 s18, s4, s20
	s_mov_b64 s[26:27], 0x1000
	s_mov_b64 s[24:25], 0x1800
	v_lshlrev_b32_e32 v52, 4, v0
	v_mov_b32_e32 v53, v193
	s_addc_u32 s19, s5, s21
	global_load_dwordx4 v[100:103], v[40:41], off offset:16
	global_load_dwordx4 v[104:107], v[40:41], off
	global_load_dwordx4 v[108:111], v[40:41], off offset:2064
	global_load_dwordx4 v[112:115], v[40:41], off offset:2048
	global_load_dwordx4 v[116:119], v[42:43], off offset:16
	global_load_dwordx4 v[120:123], v[42:43], off
	global_load_dwordx4 v[124:127], v[44:45], off offset:16
	global_load_dwordx4 v[128:131], v[44:45], off
	s_andn2_b64 vcc, exec, s[10:11]
	s_cbranch_vccnz .Lrp_b_nog
	global_load_dwordx4 v[132:135], v[46:47], off offset:16
	global_load_dwordx4 v[136:139], v[46:47], off
	global_load_dwordx4 v[140:143], v[46:47], off offset:2064
	global_load_dwordx4 v[144:147], v[46:47], off offset:2048
	global_load_dwordx4 v[148:151], v[48:49], off offset:16
	global_load_dwordx4 v[152:155], v[48:49], off
	global_load_dwordx4 v[156:159], v[50:51], off offset:16
	global_load_dwordx4 v[160:163], v[50:51], off

.LBB0_746:
	v_lshl_add_u64 v[0:1], s[12:13], 0, v[192:193]
	v_add_co_u32_e32 v4, vcc, 0x1000, v0
	v_lshl_add_u64 v[32:33], s[16:17], 0, v[52:53]
	s_nop 0
	v_addc_co_u32_e32 v5, vcc, 0, v1, vcc
	v_add_co_u32_e32 v34, vcc, 0x1ba00000, v32
	global_load_dwordx4 v[8:11], v[0:1], off offset:16
	global_load_dwordx4 v[12:15], v[0:1], off
	global_load_dwordx4 v[16:19], v[0:1], off offset:2064
	global_load_dwordx4 v[20:23], v[0:1], off offset:2048
	v_lshl_add_u64 v[2:3], v[0:1], 0, s[26:27]
	v_lshl_add_u64 v[0:1], v[0:1], 0, s[24:25]
	v_addc_co_u32_e32 v35, vcc, 0, v33, vcc
	global_load_dwordx4 v[28:31], v[4:5], off
	global_load_dwordx4 v[24:27], v[2:3], off offset:16
	s_nop 0
	global_load_dwordx4 v[4:7], v[4:5], off offset:2048
	s_nop 0
	global_load_dwordx4 v[0:3], v[0:1], off offset:16
	s_nop 0
	global_load_dwordx4 v[64:67], v[34:35], off
	global_load_dwordx4 v[68:71], v[34:35], off offset:1024
	global_load_dwordx4 v[58:61], v[34:35], off offset:2048
	global_load_dwordx4 v[82:85], v[34:35], off offset:3072
	s_mov_b32 s4, 0xf800000
	s_waitcnt vmcnt(3)
	v_and_b32_e32 v75, 0xffff0000, v66
	v_and_b32_e32 v74, 0xffff0000, v64
	v_and_b32_e32 v79, 0xffff0000, v67
	v_and_b32_e32 v78, 0xffff0000, v65
	v_lshlrev_b32_e32 v73, 16, v66
	v_lshlrev_b32_e32 v72, 16, v64
	v_lshlrev_b32_e32 v77, 16, v67
	v_lshlrev_b32_e32 v76, 16, v65
	v_pk_mul_f32 v[34:35], v[74:75], v[74:75]
	v_pk_mul_f32 v[64:65], v[78:79], v[78:79]
	v_pk_fma_f32 v[34:35], v[72:73], v[72:73], v[34:35]
	v_pk_fma_f32 v[64:65], v[76:77], v[76:77], v[64:65]
	s_waitcnt vmcnt(2)
	v_lshlrev_b32_e32 v32, 16, v70
	v_pk_add_f32 v[34:35], v[34:35], v[64:65]
	v_and_b32_e32 v33, 0xffff0000, v70
	v_pk_add_f32 v[64:65], v[34:35], v[34:35] op_sel_hi:[0,1]
	v_lshlrev_b32_e32 v35, 16, v69
	v_lshlrev_b32_e32 v34, 16, v68
	v_and_b32_e32 v69, 0xffff0000, v69
	v_and_b32_e32 v68, 0xffff0000, v68
	s_waitcnt vmcnt(1)
	v_lshlrev_b32_e32 v36, 16, v58
	v_pk_mul_f32 v[66:67], v[68:69], v[68:69]
	v_lshlrev_b32_e32 v70, 16, v71
	s_waitcnt vmcnt(0)
	v_lshlrev_b32_e32 v56, 16, v84
	v_and_b32_e32 v63, 0xffff0000, v84
	v_lshlrev_b32_e32 v54, 16, v85
	v_and_b32_e32 v55, 0xffff0000, v85
	v_pk_fma_f32 v[66:67], v[34:35], v[34:35], v[66:67]
	v_mul_f32_e32 v37, v32, v32
	v_mul_f32_e32 v85, v33, v33
	v_and_b32_e32 v71, 0xffff0000, v71
	v_mul_f32_e32 v62, v70, v70
	v_mov_b32_e32 v84, v36
	v_and_b32_e32 v80, 0xffff0000, v58
	v_lshlrev_b32_e32 v38, 16, v59
	v_and_b32_e32 v39, 0xffff0000, v59
	v_pk_add_f32 v[66:67], v[66:67], v[66:67] op_sel_hi:[0,1]
	v_pk_fma_f32 v[86:87], v[70:71], v[70:71], v[62:63] op_sel_hi:[1,1,0]
	v_pk_add_f32 v[84:85], v[36:37], v[84:85]
	v_mul_f32_e32 v86, v80, v80
	v_mul_f32_e32 v64, v38, v38
	v_mul_f32_e32 v66, v39, v39
	v_mul_f32_e32 v88, v36, v36
	v_mov_b32_e32 v89, v85
	v_pk_add_f32 v[84:85], v[88:89], v[86:87]
	v_pk_add_f32 v[64:65], v[64:65], v[66:67]
	v_and_b32_e32 v67, 0xffff0000, v61
	v_pk_add_f32 v[64:65], v[84:85], v[64:65]
	v_and_b32_e32 v66, 0xffff0000, v60
	v_pk_add_f32 v[84:85], v[64:65], v[64:65] op_sel_hi:[0,1]
	v_lshlrev_b32_e32 v65, 16, v61
	v_lshlrev_b32_e32 v64, 16, v60
	v_pk_mul_f32 v[60:61], v[66:67], v[66:67]
	v_lshlrev_b32_e32 v58, 16, v82
	v_pk_fma_f32 v[60:61], v[64:65], v[64:65], v[60:61]
	v_and_b32_e32 v59, 0xffff0000, v82
	v_pk_add_f32 v[86:87], v[60:61], v[60:61] op_sel_hi:[0,1]
	v_lshlrev_b32_e32 v60, 16, v83
	v_mul_f32_e32 v57, v58, v58
	v_mul_f32_e32 v89, v59, v59
	v_and_b32_e32 v61, 0xffff0000, v83
	v_mul_f32_e32 v62, v60, v60
	v_mov_b32_e32 v88, v56
	v_pk_fma_f32 v[82:83], v[60:61], v[60:61], v[62:63] op_sel_hi:[1,1,0]
	v_pk_add_f32 v[88:89], v[56:57], v[88:89]
	v_mul_f32_e32 v82, v63, v63
	v_mul_f32_e32 v86, v54, v54
	v_mul_f32_e32 v84, v55, v55
	v_mul_f32_e32 v90, v56, v56
	v_mov_b32_e32 v91, v89
	v_pk_add_f32 v[82:83], v[90:91], v[82:83]
	v_pk_add_f32 v[84:85], v[86:87], v[84:85]
	v_mov_b32_e32 v90, v72
	v_pk_add_f32 v[82:83], v[82:83], v[84:85]
	v_mov_b32_e32 v91, v74
	v_add_f32_e32 v37, v82, v83
	ds_bpermute_b32 v57, v230, v37
	v_mov_b32_e32 v74, v73
	s_waitcnt lgkmcnt(0)
	v_add_f32_e32 v37, v37, v57
	ds_bpermute_b32 v57, v231, v37
	s_waitcnt lgkmcnt(0)
	v_add_f32_e32 v37, v37, v57
	ds_bpermute_b32 v57, v232, v37
	s_waitcnt lgkmcnt(0)
	v_add_f32_e32 v37, v37, v57
	ds_bpermute_b32 v57, v233, v37
	s_waitcnt lgkmcnt(0)
	v_add_f32_e32 v37, v37, v57
	ds_bpermute_b32 v57, v234, v37
	s_waitcnt lgkmcnt(0)
	v_add_f32_e32 v37, v37, v57
	ds_bpermute_b32 v57, v235, v37
	s_waitcnt lgkmcnt(0)
	v_add_f32_e32 v37, v37, v57
	v_fmamk_f32 v37, v37, 0x3a000000, v219
	v_cmp_gt_f32_e32 vcc, s4, v37
	v_mul_f32_e32 v57, 0x4f800000, v37
	s_nop 0
	v_cndmask_b32_e32 v37, v37, v57, vcc
	v_sqrt_f32_e32 v57, v37
	s_nop 0
	v_add_u32_e32 v62, -1, v57
	v_fma_f32 v81, -v62, v57, v37
	v_cmp_ge_f32_e64 s[4:5], 0, v81
	v_add_u32_e32 v81, 1, v57
	s_nop 0
	v_cndmask_b32_e64 v62, v57, v62, s[4:5]
	v_fma_f32 v57, -v81, v57, v37
	v_cmp_lt_f32_e64 s[4:5], 0, v57
	s_nop 1
	v_cndmask_b32_e64 v57, v62, v81, s[4:5]
	v_mul_f32_e32 v62, 0x37800000, v57
	v_cndmask_b32_e32 v57, v57, v62, vcc
	v_cmp_class_f32_e32 vcc, v37, v220
	s_nop 1
	v_cndmask_b32_e32 v37, v57, v37, vcc
	v_div_scale_f32 v57, s[4:5], v37, v37, 1.0
	v_rcp_f32_e32 v62, v57
	s_nop 0
	v_fma_f32 v81, -v57, v62, 1.0
	v_fmac_f32_e32 v62, v81, v62
	v_div_scale_f32 v81, vcc, 1.0, v37, 1.0
	v_mul_f32_e32 v82, v81, v62
	v_fma_f32 v83, -v57, v82, v81
	v_fmac_f32_e32 v82, v83, v62
	v_fma_f32 v57, -v57, v82, v81
	v_div_fmas_f32 v57, v57, v62, v82
	v_mov_b64_e32 v[82:83], v[100:101]
	v_mov_b64_e32 v[84:85], v[102:103]
	v_mov_b64_e32 v[86:87], v[104:105]
	v_mov_b64_e32 v[88:89], v[106:107]
	v_div_fixup_f32 v62, v57, v37, 1.0
	v_mov_b32_e32 v37, v80
	v_mov_b32_e32 v57, v63
	s_andn2_b64 vcc, exec, s[8:9]
	v_pk_mul_f32 v[72:73], v[82:83], v[74:75]
	v_pk_mul_f32 v[86:87], v[86:87], v[90:91]
	v_mov_b32_e32 v91, v78
	v_mov_b32_e32 v78, v77
	v_pk_mul_f32 v[74:75], v[84:85], v[78:79]
	v_mov_b32_e32 v90, v76
	v_pk_fma_f32 v[10:11], v[74:75], v[62:63], v[10:11] op_sel_hi:[1,0,1]
	v_pk_fma_f32 v[8:9], v[72:73], v[62:63], v[8:9] op_sel_hi:[1,0,1]
	v_mov_b64_e32 v[72:73], v[108:109]
	v_mov_b64_e32 v[74:75], v[110:111]
	v_mov_b64_e32 v[76:77], v[112:113]
	v_mov_b64_e32 v[78:79], v[114:115]
	v_mov_b32_e32 v83, v68
	v_mov_b32_e32 v68, v35
	v_mov_b32_e32 v82, v34
	v_pk_mul_f32 v[88:89], v[88:89], v[90:91]
	v_pk_fma_f32 v[12:13], v[86:87], v[62:63], v[12:13] op_sel_hi:[1,0,1]
	v_pk_fma_f32 v[14:15], v[88:89], v[62:63], v[14:15] op_sel_hi:[1,0,1]
	v_pk_mul_f32 v[32:33], v[72:73], v[32:33]
	v_pk_mul_f32 v[34:35], v[78:79], v[68:69]
	v_pk_fma_f32 v[16:17], v[32:33], v[62:63], v[16:17] op_sel_hi:[1,0,1]
	v_pk_fma_f32 v[22:23], v[34:35], v[62:63], v[22:23] op_sel_hi:[1,0,1]
	v_pk_mul_f32 v[34:35], v[74:75], v[70:71]
	v_pk_mul_f32 v[76:77], v[76:77], v[82:83]
	v_pk_fma_f32 v[18:19], v[34:35], v[62:63], v[18:19] op_sel_hi:[1,0,1]
	v_mov_b64_e32 v[32:33], v[116:117]
	v_mov_b64_e32 v[34:35], v[118:119]
	v_mov_b64_e32 v[68:69], v[120:121]
	v_mov_b64_e32 v[70:71], v[122:123]
	v_pk_fma_f32 v[20:21], v[76:77], v[62:63], v[20:21] op_sel_hi:[1,0,1]
	v_pk_mul_f32 v[36:37], v[68:69], v[36:37]
	s_nop 0
	v_pk_fma_f32 v[28:29], v[36:37], v[62:63], v[28:29] op_sel_hi:[1,0,1]
	v_mov_b32_e32 v36, v64
	v_mov_b32_e32 v37, v66
	v_mov_b32_e32 v66, v65
	v_pk_mul_f32 v[38:39], v[70:71], v[38:39]
	v_pk_mul_f32 v[32:33], v[32:33], v[36:37]
	v_pk_mul_f32 v[34:35], v[34:35], v[66:67]
	v_pk_fma_f32 v[30:31], v[38:39], v[62:63], v[30:31] op_sel_hi:[1,0,1]
	v_pk_fma_f32 v[26:27], v[34:35], v[62:63], v[26:27] op_sel_hi:[1,0,1]
	v_pk_fma_f32 v[24:25], v[32:33], v[62:63], v[24:25] op_sel_hi:[1,0,1]
	v_mov_b64_e32 v[32:33], v[124:125]
	v_mov_b64_e32 v[34:35], v[126:127]
	v_mov_b64_e32 v[36:37], v[128:129]
	v_mov_b64_e32 v[38:39], v[130:131]
	v_pk_mul_f32 v[32:33], v[32:33], v[56:57]
	v_pk_mul_f32 v[36:37], v[36:37], v[58:59]
	v_pk_mul_f32 v[38:39], v[38:39], v[60:61]
	v_pk_mul_f32 v[34:35], v[34:35], v[54:55]
	v_pk_fma_f32 v[6:7], v[38:39], v[62:63], v[6:7] op_sel_hi:[1,0,1]
	v_pk_fma_f32 v[4:5], v[36:37], v[62:63], v[4:5] op_sel_hi:[1,0,1]
	v_pk_fma_f32 v[2:3], v[34:35], v[62:63], v[2:3] op_sel_hi:[1,0,1]
	v_pk_fma_f32 v[0:1], v[32:33], v[62:63], v[0:1] op_sel_hi:[1,0,1]
	s_cbranch_vccnz .LBB0_748
	v_lshl_add_u64 v[32:33], s[18:19], 0, v[192:193]
	global_store_dwordx4 v[32:33], v[12:15], off
	global_store_dwordx4 v[32:33], v[8:11], off offset:16
	global_store_dwordx4 v[32:33], v[20:23], off offset:2048
	global_store_dwordx4 v[32:33], v[16:19], off offset:2064
	v_add_co_u32_e32 v32, vcc, 0x1000, v32
	s_nop 1
	v_addc_co_u32_e32 v33, vcc, 0, v33, vcc
	global_store_dwordx4 v[32:33], v[28:31], off
	global_store_dwordx4 v[32:33], v[24:27], off offset:16
	global_store_dwordx4 v[32:33], v[4:7], off offset:2048
	global_store_dwordx4 v[32:33], v[0:3], off offset:2064
.LBB0_748:
	s_andn2_b64 vcc, exec, s[10:11]
	s_cbranch_vccnz .LBB0_745
	v_mov_b32_e32 v34, v13
	v_mov_b32_e32 v35, v9
	v_mov_b32_e32 v32, v12
	v_mov_b32_e32 v33, v8
	v_pk_mul_f32 v[34:35], v[34:35], v[34:35]
	v_mov_b32_e32 v36, v15
	v_mov_b32_e32 v37, v11
	v_pk_fma_f32 v[32:33], v[32:33], v[32:33], v[34:35]
	v_mov_b32_e32 v34, v14
	v_mov_b32_e32 v35, v10
	v_pk_mul_f32 v[36:37], v[36:37], v[36:37]
	s_mov_b32 s4, 0xf800000
	v_pk_fma_f32 v[34:35], v[34:35], v[34:35], v[36:37]
	v_pk_mul_f32 v[36:37], v[20:21], v[20:21]
	v_pk_add_f32 v[32:33], v[32:33], v[34:35]
	v_pk_mul_f32 v[34:35], v[22:23], v[22:23]
	v_pk_add_f32 v[32:33], v[32:33], v[32:33] op_sel_hi:[0,1]
	v_pk_mov_b32 v[38:39], v[36:37], v[34:35] op_sel:[1,0]
	v_mov_b32_e32 v37, v35
	v_mul_f32_e32 v32, v16, v16
	v_pk_add_f32 v[34:35], v[38:39], v[36:37]
	v_pk_fma_f32 v[36:37], v[16:17], v[16:17], v[32:33] op_sel_hi:[1,1,0]
	v_mul_f32_e32 v32, v18, v18
	v_pk_add_f32 v[34:35], v[34:35], v[34:35] op_sel_hi:[0,1]
	v_pk_fma_f32 v[38:39], v[18:19], v[18:19], v[32:33] op_sel_hi:[1,1,0]
	v_mul_f32_e32 v36, v28, v28
	v_mul_f32_e32 v38, v29, v29
	v_mul_f32_e32 v34, v30, v30
	v_mul_f32_e32 v32, v31, v31
	v_pk_add_f32 v[36:37], v[36:37], v[38:39]
	v_pk_add_f32 v[32:33], v[34:35], v[32:33]
	v_pk_mul_f32 v[34:35], v[26:27], v[26:27]
	v_pk_add_f32 v[32:33], v[36:37], v[32:33]
	v_pk_mul_f32 v[36:37], v[24:25], v[24:25]
	v_pk_add_f32 v[32:33], v[32:33], v[32:33] op_sel_hi:[0,1]
	v_pk_mov_b32 v[38:39], v[36:37], v[34:35] op_sel:[1,0]
	v_mov_b32_e32 v37, v35
	v_mul_f32_e32 v32, v4, v4
	v_pk_add_f32 v[34:35], v[38:39], v[36:37]
	v_pk_fma_f32 v[36:37], v[4:5], v[4:5], v[32:33] op_sel_hi:[1,1,0]
	v_mul_f32_e32 v32, v6, v6
	v_pk_add_f32 v[34:35], v[34:35], v[34:35] op_sel_hi:[0,1]
	v_pk_fma_f32 v[38:39], v[6:7], v[6:7], v[32:33] op_sel_hi:[1,1,0]
	v_mul_f32_e32 v36, v0, v0
	v_mul_f32_e32 v38, v1, v1
	v_mul_f32_e32 v34, v2, v2
	v_mul_f32_e32 v32, v3, v3
	v_pk_add_f32 v[36:37], v[36:37], v[38:39]
	v_pk_add_f32 v[32:33], v[34:35], v[32:33]
	v_lshl_add_u64 v[38:39], s[14:15], 0, v[52:53]
	v_pk_add_f32 v[32:33], v[36:37], v[32:33]
	s_nop 0
	v_add_f32_e32 v32, v32, v33
	ds_bpermute_b32 v33, v230, v32
	s_waitcnt lgkmcnt(0)
	v_add_f32_e32 v32, v32, v33
	ds_bpermute_b32 v33, v231, v32
	s_waitcnt lgkmcnt(0)
	v_add_f32_e32 v32, v32, v33
	ds_bpermute_b32 v33, v232, v32
	s_waitcnt lgkmcnt(0)
	v_add_f32_e32 v32, v32, v33
	ds_bpermute_b32 v33, v233, v32
	s_waitcnt lgkmcnt(0)
	v_add_f32_e32 v32, v32, v33
	ds_bpermute_b32 v33, v234, v32
	s_waitcnt lgkmcnt(0)
	v_add_f32_e32 v32, v32, v33
	ds_bpermute_b32 v33, v235, v32
	s_waitcnt lgkmcnt(0)
	v_add_f32_e32 v32, v32, v33
	v_fmamk_f32 v32, v32, 0x3a000000, v219
	v_cmp_gt_f32_e32 vcc, s4, v32
	v_mul_f32_e32 v33, 0x4f800000, v32
	s_nop 0
	v_cndmask_b32_e32 v32, v32, v33, vcc
	v_sqrt_f32_e32 v33, v32
	s_nop 0
	v_add_u32_e32 v34, -1, v33
	v_fma_f32 v35, -v34, v33, v32
	v_cmp_ge_f32_e64 s[4:5], 0, v35
	v_add_u32_e32 v35, 1, v33
	s_nop 0
	v_cndmask_b32_e64 v34, v33, v34, s[4:5]
	v_fma_f32 v33, -v35, v33, v32
	v_cmp_lt_f32_e64 s[4:5], 0, v33
	s_nop 1
	v_cndmask_b32_e64 v33, v34, v35, s[4:5]
	v_mul_f32_e32 v34, 0x37800000, v33
	v_cndmask_b32_e32 v33, v33, v34, vcc
	v_cmp_class_f32_e32 vcc, v32, v220
	s_nop 1
	v_cndmask_b32_e32 v32, v33, v32, vcc
	v_div_scale_f32 v33, s[4:5], v32, v32, 1.0
	v_rcp_f32_e32 v34, v33
	s_mov_b32 s4, 0xffff0000
	s_mov_b32 s5, 0x14200000
	v_fma_f32 v35, -v33, v34, 1.0
	v_fmac_f32_e32 v34, v35, v34
	v_div_scale_f32 v35, vcc, 1.0, v32, 1.0
	v_mul_f32_e32 v36, v35, v34
	v_fma_f32 v37, -v33, v36, v35
	v_fmac_f32_e32 v36, v37, v34
	v_fma_f32 v33, -v33, v36, v35
	v_div_fmas_f32 v33, v33, v34, v36
	v_div_fixup_f32 v36, v33, v32, 1.0
	v_mov_b64_e32 v[32:33], v[132:133]
	v_mov_b64_e32 v[34:35], v[134:135]
	v_mov_b64_e32 v[54:55], v[136:137]
	v_mov_b64_e32 v[56:57], v[138:139]
	v_pk_mul_f32 v[10:11], v[10:11], v[34:35]
	v_pk_mul_f32 v[12:13], v[12:13], v[54:55]
	v_pk_mul_f32 v[8:9], v[8:9], v[32:33]
	v_pk_mul_f32 v[12:13], v[12:13], v[36:37] op_sel_hi:[1,0]
	v_pk_mul_f32 v[32:33], v[10:11], v[36:37] op_sel_hi:[1,0]
	v_bfe_u32 v10, v12, 16, 1
	v_pk_mul_f32 v[14:15], v[14:15], v[56:57]
	v_add3_u32 v10, v12, v10, s77
	v_bfe_u32 v11, v13, 16, 1
	v_pk_mul_f32 v[14:15], v[14:15], v[36:37] op_sel_hi:[1,0]
	v_lshrrev_b32_e32 v10, 16, v10
	v_add3_u32 v11, v13, v11, s77
	v_and_or_b32 v10, v11, s4, v10
	v_bfe_u32 v11, v14, 16, 1
	v_add3_u32 v11, v14, v11, s77
	v_bfe_u32 v12, v15, 16, 1
	v_pk_mul_f32 v[8:9], v[8:9], v[36:37] op_sel_hi:[1,0]
	v_lshrrev_b32_e32 v11, 16, v11
	v_add3_u32 v12, v15, v12, s77
	v_and_or_b32 v11, v12, s4, v11
	v_bfe_u32 v12, v8, 16, 1
	v_add3_u32 v8, v8, v12, s77
	v_bfe_u32 v12, v9, 16, 1
	v_lshrrev_b32_e32 v8, 16, v8
	v_add3_u32 v9, v9, v12, s77
	v_and_or_b32 v12, v9, s4, v8
	v_bfe_u32 v8, v32, 16, 1
	v_add3_u32 v8, v32, v8, s77
	v_bfe_u32 v9, v33, 16, 1
	v_lshrrev_b32_e32 v8, 16, v8
	v_add3_u32 v9, v33, v9, s77
	v_and_or_b32 v13, v9, s4, v8
	v_add_co_u32_e32 v8, vcc, s5, v38
	s_nop 1
	v_addc_co_u32_e32 v9, vcc, 0, v39, vcc
	global_store_dwordx4 v[8:9], v[10:13], off
	s_nop 1
	v_mov_b64_e32 v[10:11], v[140:141]
	v_mov_b64_e32 v[12:13], v[142:143]
	s_nop 0
	v_mov_b64_e32 v[32:33], v[144:145]
	v_mov_b64_e32 v[34:35], v[146:147]
	v_pk_mul_f32 v[12:13], v[18:19], v[12:13]
	v_pk_mul_f32 v[20:21], v[20:21], v[32:33]
	v_pk_mul_f32 v[10:11], v[16:17], v[10:11]
	v_pk_mul_f32 v[20:21], v[20:21], v[36:37] op_sel_hi:[1,0]
	v_pk_mul_f32 v[16:17], v[12:13], v[36:37] op_sel_hi:[1,0]
	v_pk_mul_f32 v[12:13], v[10:11], v[36:37] op_sel_hi:[1,0]
	v_bfe_u32 v10, v20, 16, 1
	v_pk_mul_f32 v[14:15], v[22:23], v[34:35]
	v_add3_u32 v10, v20, v10, s77
	v_bfe_u32 v11, v21, 16, 1
	v_pk_mul_f32 v[14:15], v[14:15], v[36:37] op_sel_hi:[1,0]
	v_lshrrev_b32_e32 v10, 16, v10
	v_add3_u32 v11, v21, v11, s77
	v_and_or_b32 v10, v11, s4, v10
	v_bfe_u32 v11, v14, 16, 1
	v_add3_u32 v11, v14, v11, s77
	v_bfe_u32 v14, v15, 16, 1
	v_lshrrev_b32_e32 v11, 16, v11
	v_add3_u32 v14, v15, v14, s77
	v_and_or_b32 v11, v14, s4, v11
	v_bfe_u32 v14, v12, 16, 1
	v_add3_u32 v12, v12, v14, s77
	v_bfe_u32 v14, v13, 16, 1
	v_lshrrev_b32_e32 v12, 16, v12
	v_add3_u32 v13, v13, v14, s77
	v_and_or_b32 v12, v13, s4, v12
	v_bfe_u32 v13, v16, 16, 1
	v_add3_u32 v13, v16, v13, s77
	v_bfe_u32 v14, v17, 16, 1
	v_lshrrev_b32_e32 v13, 16, v13
	v_add3_u32 v14, v17, v14, s77
	v_and_or_b32 v13, v14, s4, v13
	global_store_dwordx4 v[8:9], v[10:13], off offset:1024
	s_nop 1
	v_mov_b64_e32 v[10:11], v[148:149]
	v_mov_b64_e32 v[12:13], v[150:151]
	s_nop 0
	v_mov_b64_e32 v[14:15], v[152:153]
	v_mov_b64_e32 v[16:17], v[154:155]
	v_pk_mul_f32 v[12:13], v[26:27], v[12:13]
	v_pk_mul_f32 v[14:15], v[28:29], v[14:15]
	v_pk_mul_f32 v[10:11], v[24:25], v[10:11]
	v_pk_mul_f32 v[14:15], v[36:37], v[14:15] op_sel_hi:[0,1]
	v_pk_mul_f32 v[18:19], v[36:37], v[12:13] op_sel_hi:[0,1]
	v_pk_mul_f32 v[12:13], v[36:37], v[10:11] op_sel_hi:[0,1]
	v_bfe_u32 v10, v14, 16, 1
	v_pk_mul_f32 v[16:17], v[30:31], v[16:17]
	v_add3_u32 v10, v14, v10, s77
	v_bfe_u32 v11, v15, 16, 1
	v_pk_mul_f32 v[16:17], v[36:37], v[16:17] op_sel_hi:[0,1]
	v_lshrrev_b32_e32 v10, 16, v10
	v_add3_u32 v11, v15, v11, s77
	v_and_or_b32 v10, v11, s4, v10
	v_bfe_u32 v11, v16, 16, 1
	v_add3_u32 v11, v16, v11, s77
	v_bfe_u32 v14, v17, 16, 1
	v_lshrrev_b32_e32 v11, 16, v11
	v_add3_u32 v14, v17, v14, s77
	v_and_or_b32 v11, v14, s4, v11
	v_bfe_u32 v14, v12, 16, 1
	v_add3_u32 v12, v12, v14, s77
	v_bfe_u32 v14, v13, 16, 1
	v_lshrrev_b32_e32 v12, 16, v12
	v_add3_u32 v13, v13, v14, s77
	v_and_or_b32 v12, v13, s4, v12
	v_bfe_u32 v13, v18, 16, 1
	v_add3_u32 v13, v18, v13, s77
	v_bfe_u32 v14, v19, 16, 1
	v_lshrrev_b32_e32 v13, 16, v13
	v_add3_u32 v14, v19, v14, s77
	v_and_or_b32 v13, v14, s4, v13
	global_store_dwordx4 v[8:9], v[10:13], off offset:2048
	s_nop 1
	v_mov_b64_e32 v[10:11], v[156:157]
	v_mov_b64_e32 v[12:13], v[158:159]
	s_nop 0
	v_mov_b64_e32 v[14:15], v[160:161]
	v_mov_b64_e32 v[16:17], v[162:163]
	v_pk_mul_f32 v[2:3], v[2:3], v[12:13]
	v_pk_mul_f32 v[4:5], v[4:5], v[14:15]
	v_pk_mul_f32 v[0:1], v[0:1], v[10:11]
	v_pk_mul_f32 v[4:5], v[36:37], v[4:5] op_sel_hi:[0,1]
	v_pk_mul_f32 v[10:11], v[36:37], v[2:3] op_sel_hi:[0,1]
	v_pk_mul_f32 v[2:3], v[36:37], v[0:1] op_sel_hi:[0,1]
	v_bfe_u32 v0, v4, 16, 1
	v_pk_mul_f32 v[6:7], v[6:7], v[16:17]
	v_add3_u32 v0, v4, v0, s77
	v_bfe_u32 v1, v5, 16, 1
	v_pk_mul_f32 v[6:7], v[36:37], v[6:7] op_sel_hi:[0,1]
	v_lshrrev_b32_e32 v0, 16, v0
	v_add3_u32 v1, v5, v1, s77
	v_and_or_b32 v0, v1, s4, v0
	v_bfe_u32 v1, v6, 16, 1
	v_add3_u32 v1, v6, v1, s77
	v_bfe_u32 v4, v7, 16, 1
	v_lshrrev_b32_e32 v1, 16, v1
	v_add3_u32 v4, v7, v4, s77
	v_and_or_b32 v1, v4, s4, v1
	v_bfe_u32 v4, v2, 16, 1
	v_add3_u32 v2, v2, v4, s77
	v_bfe_u32 v4, v3, 16, 1
	v_lshrrev_b32_e32 v2, 16, v2
	v_add3_u32 v3, v3, v4, s77
	v_and_or_b32 v2, v3, s4, v2
	v_bfe_u32 v3, v10, 16, 1
	v_add3_u32 v3, v10, v3, s77
	v_bfe_u32 v4, v11, 16, 1
	v_lshrrev_b32_e32 v3, 16, v3
	v_add3_u32 v4, v11, v4, s77
	v_and_or_b32 v3, v4, s4, v3
	global_store_dwordx4 v[8:9], v[0:3], off offset:3072
	s_branch .LBB0_745
